# attention waves run their tile loops at s_setprio 3 (conversion waves stay 0), reset at the next phase
# baseline (speedup 1.0000x reference)
.LBB0_1200:
	s_setprio 3
	s_add_i32 s37, s43, 1
	s_cmp_lt_u32 s37, s31
	s_cselect_b64 s[34:35], -1, 0
	s_cmp_ge_u32 s37, s31
	s_cbranch_scc1 .LBB0_1202
	s_cmp_lt_u32 s37, s42
	s_cselect_b32 s44, 0, s42
	s_cselect_b32 s45, s30, s41
	s_lshl_b32 s44, s44, 6
	s_sub_i32 s44, s45, s44
	s_add_i32 s44, s36, s44
	v_add_u32_e32 v2, s44, v216
	v_ashrrev_i32_e32 v3, 31, v2
	v_lshlrev_b64 v[4:5], 11, v[2:3]
	v_lshlrev_b64 v[2:3], 7, v[2:3]
	v_lshl_add_u64 v[2:3], v[188:189], 0, v[2:3]
	v_lshl_add_u64 v[4:5], v[206:207], 0, v[4:5]
	v_lshl_add_u64 v[2:3], v[2:3], 0, s[24:25]
	v_cndmask_b32_e64 v3, v3, v5, s[6:7]
	v_cndmask_b32_e64 v2, v2, v4, s[6:7]
	global_load_dwordx4 v[160:163], v[2:3], off
	v_add_u32_e32 v2, s44, v217
	v_ashrrev_i32_e32 v3, 31, v2
	v_lshlrev_b64 v[4:5], 11, v[2:3]
	v_lshlrev_b64 v[2:3], 7, v[2:3]
	v_lshl_add_u64 v[2:3], v[192:193], 0, v[2:3]
	v_lshl_add_u64 v[4:5], v[208:209], 0, v[4:5]
	v_lshl_add_u64 v[2:3], v[2:3], 0, s[24:25]
	v_cndmask_b32_e64 v3, v3, v5, s[10:11]
	v_cndmask_b32_e64 v2, v2, v4, s[10:11]
	global_load_dwordx4 v[164:167], v[2:3], off
	v_add_u32_e32 v2, s44, v218
	v_ashrrev_i32_e32 v3, 31, v2
	v_lshlrev_b64 v[4:5], 11, v[2:3]
	v_lshlrev_b64 v[2:3], 7, v[2:3]
	v_lshl_add_u64 v[2:3], v[196:197], 0, v[2:3]
	v_lshl_add_u64 v[4:5], v[210:211], 0, v[4:5]
	v_lshl_add_u64 v[2:3], v[2:3], 0, s[24:25]
	v_cndmask_b32_e64 v3, v3, v5, s[14:15]
	v_cndmask_b32_e64 v2, v2, v4, s[14:15]
	s_ashr_i32 s45, s44, 31
	global_load_dwordx4 v[168:171], v[2:3], off
	v_lshl_add_u64 v[2:3], s[44:45], 1, v[184:185]
	v_lshl_add_u64 v[4:5], v[2:3], 0, v[202:203]
	v_lshl_add_u64 v[2:3], v[2:3], 0, v[204:205]
	global_load_dwordx4 v[172:175], v[4:5], off
	global_load_dwordx4 v[176:179], v[2:3], off

.LBB0_1263:
	s_setprio 0
	s_cmp_lt_i32 s56, 7
	s_cselect_b64 s[8:9], -1, 0
	s_and_b64 s[6:7], s[8:9], s[6:7]
	s_andn2_b64 vcc, exec, s[6:7]
	s_cbranch_vccnz .LBB0_1335
	v_mbcnt_hi_u32_b32 v140, -1, v254
	s_waitcnt vmcnt(0)
	v_mov_b32_e32 v0, v140
	s_cmpk_gt_i32 s92, 0x17f
	s_cbranch_scc1 .LBB0_1280
	s_lshl_b32 s3, s33, 10
	v_lshl_add_u32 v1, v0, 4, s3
	v_add_u32_e32 v2, 0x2000, v1
	v_ashrrev_i32_e32 v3, 31, v2
	v_lshrrev_b32_e32 v3, 22, v3
	v_add_u32_e32 v3, v2, v3
	v_ashrrev_i32_e32 v3, 10, v3
	v_mul_i32_i24_e32 v5, 0x400, v3
	v_sub_u32_e32 v2, v2, v5
	v_lshrrev_b32_e32 v5, 4, v2
	v_bitop3_b32 v2, v5, v2, 32 bitop3:0x6c
	v_ashrrev_i32_e32 v5, 31, v2
	v_lshrrev_b32_e32 v5, 26, v5
	v_add_u32_e32 v5, v2, v5
	v_ashrrev_i32_e32 v6, 6, v5
	v_and_b32_e32 v5, 0xffc0, v5
	v_sub_u32_e32 v2, v2, v5
	v_lshrrev_b16_e32 v5, 7, v2
	v_lshlrev_b32_e32 v4, 5, v3
	v_and_b32_e32 v5, 1, v5
	v_lshlrev_b32_e32 v3, 3, v3
	v_add_u16_e32 v2, v2, v5
	v_mov_b32_e32 v5, 1
	v_and_b32_e32 v3, -16, v3
	v_and_b32_e32 v4, 32, v4
	v_ashrrev_i16_sdwa v2, v5, sext(v2) dst_sel:DWORD dst_unused:UNUSED_PAD src0_sel:DWORD src1_sel:BYTE_0
	v_add_u32_e32 v3, v6, v3
	v_add_u32_sdwa v2, v4, sext(v2) dst_sel:DWORD dst_unused:UNUSED_PAD src0_sel:DWORD src1_sel:WORD_0
	v_and_b32_e32 v4, 3, v6
	s_mov_b32 s9, 0xfffffe0
	v_lshrrev_b32_e32 v6, 2, v3
	v_lshlrev_b32_e32 v7, 1, v3
	v_and_or_b32 v4, v3, s9, v4
	v_and_b32_e32 v6, 4, v6
	v_and_b32_e32 v7, 24, v7
	v_or3_b32 v4, v4, v6, v7
	v_ashrrev_i32_e32 v6, 31, v1
	v_lshrrev_b32_e32 v6, 22, v6
	v_add_u32_e32 v6, v1, v6
	v_ashrrev_i32_e32 v6, 10, v6
	v_mul_i32_i24_e32 v8, 0x400, v6
	v_sub_u32_e32 v1, v1, v8
	v_lshrrev_b32_e32 v8, 4, v1
	v_bitop3_b32 v1, v8, v1, 32 bitop3:0x6c
	v_ashrrev_i32_e32 v8, 31, v1
	v_lshrrev_b32_e32 v8, 26, v8
	s_load_dwordx2 s[12:13], s[0:1], 0xf0
	v_add_u32_e32 v8, v1, v8
	v_ashrrev_i32_e32 v9, 6, v8
	v_and_b32_e32 v8, 0xc0, v8
	v_sub_u32_e32 v1, v1, v8
	s_lshr_b32 s8, s90, 8
	v_ashrrev_i16_sdwa v1, v5, sext(v1) dst_sel:DWORD dst_unused:UNUSED_PAD src0_sel:DWORD src1_sel:BYTE_0
	v_lshlrev_b32_e32 v5, 3, v6
	s_ashr_i32 s40, s92, 3
	s_and_b32 s76, s92, 7
	v_lshlrev_b32_e32 v7, 5, v6
	v_and_b32_e32 v5, -16, v5
	s_waitcnt lgkmcnt(0)
	s_add_u32 s27, s12, 0x471d8000
	v_and_b32_e32 v7, 32, v7
	v_add_u32_e32 v5, v9, v5
	v_and_b32_e32 v6, 3, v9
	s_addc_u32 s29, s13, 0
	s_ashr_i32 s41, s40, 31
	v_add_u32_sdwa v1, v7, sext(v1) dst_sel:DWORD dst_unused:UNUSED_PAD src0_sel:DWORD src1_sel:WORD_0
	v_and_or_b32 v6, v5, s9, v6
	v_lshrrev_b32_e32 v7, 2, v5
	v_lshlrev_b32_e32 v8, 1, v5
	s_lshl_b64 s[10:11], s[40:41], 19
	v_lshlrev_b32_e32 v5, 11, v5
	v_and_b32_e32 v7, 4, v7
	v_and_b32_e32 v8, 24, v8
	s_add_u32 s42, s27, s10
	v_lshl_add_u32 v141, v1, 1, v5
	v_lshlrev_b32_e32 v1, 12, v1
	v_or3_b32 v6, v6, v7, v8
	s_addc_u32 s43, s29, s11
	v_and_b32_e32 v1, 0xffff8000, v1
	s_add_u32 s41, s12, 0x19d8000
	v_lshl_add_u32 v143, v6, 4, v1
	v_lshlrev_b32_e32 v1, 12, v2
	s_addc_u32 s52, s13, 0
	s_lshl_b32 s9, s76, 12
	v_and_b32_e32 v1, 0xffff8000, v1
	s_add_u32 s44, s41, s9
	v_lshlrev_b32_e32 v3, 11, v3
	v_lshl_add_u32 v144, v4, 4, v1
	s_addc_u32 s45, s52, 0
	v_lshl_add_u32 v142, v2, 1, v3
	v_mov_b32_e32 v1, v144
	v_mov_b32_e32 v2, v143
	s_add_i32 s53, s3, 0
	s_add_i32 m0, s53, 0x10000
	v_mov_b32_e32 v128, v143
	global_load_lds_dwordx4 v2, s[44:45]
	s_add_i32 m0, s53, 0x12000
	v_mov_b32_e32 v2, v144
	v_mov_b32_e32 v129, 0
	global_load_lds_dwordx4 v1, s[44:45]
	s_mov_b64 s[14:15], 0x800
	v_lshl_add_u64 v[4:5], s[44:45], 0, v[128:129]
	v_mov_b32_e32 v3, v129
	v_lshl_add_u64 v[4:5], v[4:5], 0, s[14:15]
	s_add_i32 m0, s53, 0x14000
	v_lshl_add_u64 v[2:3], s[44:45], 0, v[2:3]
	global_load_lds_dwordx4 v[4:5], off
	v_lshl_add_u64 v[2:3], v[2:3], 0, s[14:15]
	s_add_i32 m0, s53, 0x16000
	s_add_i32 s54, s53, 0x2000
	global_load_lds_dwordx4 v[2:3], off
	v_mov_b32_e32 v1, v141
	v_mov_b32_e32 v2, v142
	s_mov_b32 m0, s53
	s_add_u32 s10, s42, 0x40000
	s_addc_u32 s11, s43, 0
	global_load_lds_dwordx4 v1, s[42:43]
	s_mov_b32 m0, s54
	s_add_i32 s55, s53, 0x4000
	global_load_lds_dwordx4 v2, s[42:43]
	v_mov_b32_e32 v1, v141
	v_mov_b32_e32 v2, v142
	s_mov_b32 m0, s55
	s_add_i32 s63, s53, 0x6000
	s_cmp_eq_u32 s8, 1
	global_load_lds_dwordx4 v1, s[10:11]
	s_mov_b32 m0, s63
	s_cselect_b64 s[16:17], -1, 0
	global_load_lds_dwordx4 v2, s[10:11]
	s_cmp_lg_u32 s8, 1
	s_cbranch_scc1 .LBB0_1267
	s_barrier

.LBB0_2407:
	s_setprio 3
	s_add_i32 s30, s20, 1
	s_cmp_lt_i32 s30, s28
	s_cselect_b64 s[18:19], -1, 0
	s_cmp_ge_i32 s30, s28
	s_cbranch_scc1 .LBB0_2409
	s_cmp_lt_i32 s30, s26
	s_cselect_b32 s21, 0, s26
	s_cselect_b32 s31, s25, s27
	s_lshl_b32 s21, s21, 6
	s_sub_i32 s21, s31, s21
	s_add_i32 s34, s29, s21
	v_add_u32_e32 v66, s34, v196
	v_ashrrev_i32_e32 v67, 31, v66
	v_lshlrev_b64 v[66:67], 9, v[66:67]
	v_lshl_add_u64 v[66:67], v[190:191], 0, v[66:67]
	s_ashr_i32 s35, s34, 31
	v_lshl_add_u64 v[68:69], s[34:35], 1, v[192:193]
	global_load_dwordx4 v[162:165], v[66:67], off
	global_load_dwordx4 v[166:169], v[68:69], off

.LBB0_2477:
	s_setprio 0
	s_cmp_lt_i32 s56, 15
	s_cselect_b64 s[6:7], -1, 0
	s_and_b64 s[6:7], s[6:7], s[8:9]
	s_andn2_b64 vcc, exec, s[6:7]
	s_cbranch_vccnz .LBB0_2549
	s_waitcnt vmcnt(0)
	v_mbcnt_hi_u32_b32 v140, -1, v254
	v_mov_b32_e32 v0, v140
	s_cmpk_gt_i32 s92, 0x17f
	s_cbranch_scc1 .LBB0_2494
	s_lshl_b32 s3, s33, 10
	v_lshl_add_u32 v1, v0, 4, s3
	v_add_u32_e32 v2, 0x2000, v1
	v_ashrrev_i32_e32 v3, 31, v2
	v_lshrrev_b32_e32 v3, 22, v3
	v_add_u32_e32 v3, v2, v3
	v_ashrrev_i32_e32 v3, 10, v3
	v_mul_i32_i24_e32 v5, 0x400, v3
	v_sub_u32_e32 v2, v2, v5
	v_lshrrev_b32_e32 v5, 4, v2
	v_bitop3_b32 v2, v5, v2, 32 bitop3:0x6c
	v_ashrrev_i32_e32 v5, 31, v2
	v_lshrrev_b32_e32 v5, 26, v5
	v_add_u32_e32 v5, v2, v5
	v_ashrrev_i32_e32 v6, 6, v5
	v_and_b32_e32 v5, 0xffc0, v5
	v_sub_u32_e32 v2, v2, v5
	v_lshrrev_b16_e32 v5, 7, v2
	v_lshlrev_b32_e32 v4, 5, v3
	v_and_b32_e32 v5, 1, v5
	v_lshlrev_b32_e32 v3, 3, v3
	v_add_u16_e32 v2, v2, v5
	v_mov_b32_e32 v5, 1
	v_and_b32_e32 v3, -16, v3
	v_and_b32_e32 v4, 32, v4
	v_ashrrev_i16_sdwa v2, v5, sext(v2) dst_sel:DWORD dst_unused:UNUSED_PAD src0_sel:DWORD src1_sel:BYTE_0
	v_add_u32_e32 v3, v6, v3
	v_add_u32_sdwa v2, v4, sext(v2) dst_sel:DWORD dst_unused:UNUSED_PAD src0_sel:DWORD src1_sel:WORD_0
	v_and_b32_e32 v4, 3, v6
	s_mov_b32 s8, 0xfffffe0
	v_lshrrev_b32_e32 v6, 2, v3
	v_lshlrev_b32_e32 v7, 1, v3
	v_and_or_b32 v4, v3, s8, v4
	v_and_b32_e32 v6, 4, v6
	v_and_b32_e32 v7, 24, v7
	v_or3_b32 v4, v4, v6, v7
	v_ashrrev_i32_e32 v6, 31, v1
	v_lshrrev_b32_e32 v6, 22, v6
	v_add_u32_e32 v6, v1, v6
	v_ashrrev_i32_e32 v6, 10, v6
	v_mul_i32_i24_e32 v8, 0x400, v6
	v_sub_u32_e32 v1, v1, v8
	v_lshrrev_b32_e32 v8, 4, v1
	v_bitop3_b32 v1, v8, v1, 32 bitop3:0x6c
	v_ashrrev_i32_e32 v8, 31, v1
	v_lshrrev_b32_e32 v8, 26, v8
	v_add_u32_e32 v8, v1, v8
	v_ashrrev_i32_e32 v9, 6, v8
	v_and_b32_e32 v8, 0xc0, v8
	v_sub_u32_e32 v1, v1, v8
	v_ashrrev_i16_sdwa v1, v5, sext(v1) dst_sel:DWORD dst_unused:UNUSED_PAD src0_sel:DWORD src1_sel:BYTE_0
	v_lshlrev_b32_e32 v5, 3, v6
	v_and_b32_e32 v5, -16, v5
	v_lshlrev_b32_e32 v7, 5, v6
	v_add_u32_e32 v5, v9, v5
	v_and_b32_e32 v6, 3, v9
	v_and_or_b32 v6, v5, s8, v6
	s_load_dwordx2 s[8:9], s[0:1], 0xf0
	s_lshr_b32 s14, s90, 8
	s_ashr_i32 s38, s92, 3
	s_and_b32 s72, s92, 7
	v_and_b32_e32 v7, 32, v7
	s_waitcnt lgkmcnt(0)
	s_add_u32 s25, s8, 0x471d8000
	s_addc_u32 s27, s9, 0
	s_ashr_i32 s39, s38, 31
	s_lshl_b64 s[10:11], s[38:39], 19
	v_add_u32_sdwa v1, v7, sext(v1) dst_sel:DWORD dst_unused:UNUSED_PAD src0_sel:DWORD src1_sel:WORD_0
	v_lshrrev_b32_e32 v7, 2, v5
	v_lshlrev_b32_e32 v8, 1, v5
	s_add_u32 s40, s25, s10
	v_lshlrev_b32_e32 v5, 11, v5
	v_and_b32_e32 v7, 4, v7
	v_and_b32_e32 v8, 24, v8
	s_addc_u32 s41, s27, s11
	v_lshl_add_u32 v141, v1, 1, v5
	v_lshlrev_b32_e32 v1, 12, v1
	v_or3_b32 v6, v6, v7, v8
	s_add_u32 s39, s8, 0x2bd8000
	v_and_b32_e32 v1, 0xffff8000, v1
	s_addc_u32 s46, s9, 0
	s_lshl_b32 s10, s72, 12
	v_lshl_add_u32 v143, v6, 4, v1
	v_lshlrev_b32_e32 v1, 12, v2
	s_add_u32 s42, s39, s10
	v_and_b32_e32 v1, 0xffff8000, v1
	s_addc_u32 s43, s46, 0
	v_lshlrev_b32_e32 v3, 11, v3
	v_lshl_add_u32 v144, v4, 4, v1
	s_add_i32 s47, s3, 0
	v_lshl_add_u32 v142, v2, 1, v3
	v_mov_b32_e32 v1, v143
	v_mov_b32_e32 v2, v144
	s_add_i32 m0, s47, 0x10000
	v_mov_b32_e32 v128, v143
	global_load_lds_dwordx4 v1, s[42:43]
	s_add_i32 m0, s47, 0x12000
	v_mov_b32_e32 v129, 0
	global_load_lds_dwordx4 v2, s[42:43]
	v_mov_b32_e32 v2, v144
	s_mov_b64 s[10:11], 0x800
	v_lshl_add_u64 v[4:5], s[42:43], 0, v[128:129]
	v_mov_b32_e32 v3, v129
	v_lshl_add_u64 v[4:5], v[4:5], 0, s[10:11]
	s_add_i32 m0, s47, 0x14000
	v_lshl_add_u64 v[2:3], s[42:43], 0, v[2:3]
	global_load_lds_dwordx4 v[4:5], off
	v_lshl_add_u64 v[2:3], v[2:3], 0, s[10:11]
	s_add_i32 m0, s47, 0x16000
	s_add_i32 s50, s47, 0x2000
	global_load_lds_dwordx4 v[2:3], off
	v_mov_b32_e32 v1, v141
	v_mov_b32_e32 v2, v142
	s_mov_b32 m0, s47
	s_add_u32 s12, s40, 0x40000
	s_addc_u32 s13, s41, 0
	global_load_lds_dwordx4 v1, s[40:41]
	s_mov_b32 m0, s50
	s_add_i32 s51, s47, 0x4000
	global_load_lds_dwordx4 v2, s[40:41]
	v_mov_b32_e32 v1, v141
	v_mov_b32_e32 v2, v142
	s_mov_b32 m0, s51
	s_add_i32 s52, s47, 0x6000
	s_cmp_eq_u32 s14, 1
	global_load_lds_dwordx4 v1, s[12:13]
	s_mov_b32 m0, s52
	s_nop 0
	global_load_lds_dwordx4 v2, s[12:13]
	s_cselect_b64 s[12:13], -1, 0
	s_cmp_lg_u32 s14, 1
	s_cbranch_scc1 .LBB0_2481
	s_barrier
